# split-K FFN2 ctx epilogue (EpiResidAtomic): gate load hoisted, no per-row-group vmcnt(0) waiting on the previous float atomics
# baseline (speedup 1.0000x reference)
;   DI void operator()(int m, int n, f32x4 v) const {
;     const int row = m + row0;
;     float* d = row < TL ? dl + (size_t)row * DM : dc + (size_t)(row - TL) * DM;
;     const int mi = row < TL ? (row >> 14) : 2;
;     const f32x4 g = *(const f32x4*)(gate + mi * 6144 + n);
; #pragma unroll
;     for (int j = 0; j < 4; ++j) unsafeAtomicAdd(d + n + j, g[j] * v[j]);
;   }
; template <class Epi>
; DI void gemm_phase512(const bf16_t* A, const bf16_t* Bt, int mtiles, int ntiles, int K, int Kper, int ksplit, const Epi& epi,
;                       unsigned char* smem, int bid, int nb) {
;     ...
;       } else {
; #pragma unroll
;         for (int half = 0; half < 2; ++half) {
;           if (half) asm volatile("" ::: "memory");
; #pragma unroll
;           for (int ni = 0; ni < 2; ++ni)
; #pragma unroll
;             for (int mh = 0; mh < 2; ++mh)
; #pragma unroll
;               for (int g = 0; g < 4; ++g) {
;                 const int mi = 2 * half + mh;
;                 f32x4 v = {acc[ni][mi][4 * g], acc[ni][mi][4 * g + 1], acc[ni][mi][4 * g + 2], acc[ni][mi][4 * g + 3]};
;                 *(f32x4*)(wl + (mh * 32 + l31) * 272 + (ni * 32 + 8 * g + 4 * hh) * 4) = v;
;               }
;           asm volatile("" ::: "memory");
; #pragma unroll
;           for (int i = 0; i < 16; ++i) {
;             const int row = (lane >> 4) + 4 * i, ch = lane & 15;
;             const f32x4 v = *(const f32x4*)(wl + row * 272 + ch * 16);
;             epi(m0 + half * 64 + row, n0 + ch * 4, v);
;           }
.LBB0_762:
	s_waitcnt vmcnt(5)
	v_add_co_u32_e32 v132, vcc, 0x80000, v162
	v_lshl_or_b32 v189, s26, 8, v167
	s_nop 0
	v_addc_co_u32_e32 v133, vcc, 0, v163, vcc
	s_waitcnt vmcnt(3)
	v_add_co_u32_e32 v136, vcc, 0x80000, v164
	global_load_dwordx4 v[128:131], v[162:163], off
	s_nop 0
	v_addc_co_u32_e32 v137, vcc, 0, v165, vcc
	v_add_co_u32_e32 v140, vcc, 0x100000, v162
	global_load_dwordx4 v[132:135], v[132:133], off
	s_nop 0
	v_addc_co_u32_e32 v141, vcc, 0, v163, vcc
	s_waitcnt vmcnt(3)
	v_add_co_u32_e32 v144, vcc, 0x100000, v164
	global_load_dwordx4 v[136:139], v[136:137], off
	s_nop 0
	v_addc_co_u32_e32 v145, vcc, 0, v165, vcc
	v_add_co_u32_e32 v148, vcc, 0x180000, v162
	global_load_dwordx4 v[140:143], v[140:141], off
	s_nop 0
	v_addc_co_u32_e32 v149, vcc, 0, v163, vcc
	v_add_co_u32_e32 v152, vcc, 0x180000, v164
	global_load_dwordx4 v[144:147], v[144:145], off
	s_nop 0
	v_addc_co_u32_e32 v153, vcc, 0, v165, vcc
	global_load_dwordx4 v[148:151], v[148:149], off
	s_nop 0
	global_load_dwordx4 v[156:159], v[164:165], off
	s_nop 0
	global_load_dwordx4 v[152:155], v[152:153], off
	ds_write_b128 v187, v[112:115]
	ds_write_b128 v187, v[116:119] offset:32
	ds_write_b128 v187, v[120:123] offset:64
	ds_write_b128 v187, v[124:127] offset:96
	ds_write_b128 v187, v[96:99] offset:8704
	ds_write_b128 v187, v[100:103] offset:8736
	ds_write_b128 v187, v[104:107] offset:8768
	ds_write_b128 v187, v[108:111] offset:8800
	ds_write_b128 v187, v[80:83] offset:128
	ds_write_b128 v187, v[84:87] offset:160
	ds_write_b128 v187, v[88:91] offset:192
	ds_write_b128 v187, v[92:95] offset:224
	ds_write_b128 v187, v[64:67] offset:8832
	ds_write_b128 v187, v[68:71] offset:8864
	ds_write_b128 v187, v[72:75] offset:8896
	ds_write_b128 v187, v[76:79] offset:8928
	v_lshl_add_u32 v198, s25, 8, v169
	v_ashrrev_i32_e32 v199, 31, v198
	v_or_b32_e32 v200, v189, v168
	v_add_u32_e32 v200, s46, v200
	v_lshlrev_b64 v[198:199], 2, v[198:199]
	v_cmp_gt_i32_e32 vcc, s34, v200
	v_add_u32_e32 v202, 0xffff8000, v200
	v_ashrrev_i32_e32 v203, 31, v200
	v_min_i32_e32 v204, 0x8000, v200
	v_cndmask_b32_e32 v203, 0, v203, vcc
	v_cndmask_b32_e32 v202, v202, v200, vcc
	v_ashrrev_i32_e32 v204, 14, v204
	v_lshlrev_b64 v[202:203], 12, v[202:203]
	v_mul_i32_i24_e32 v204, 0x1800, v204
	v_ashrrev_i32_e32 v205, 31, v204
	v_lshl_add_u64 v[206:207], v[204:205], 2, s[40:41]
	v_lshl_add_u64 v[206:207], v[206:207], 0, v[198:199]
	global_load_dwordx4 v[208:211], v[206:207], off
	v_mov_b32_e32 v239, s7
	v_mov_b32_e32 v201, s5
	v_mov_b32_e32 v238, s6
	v_mov_b32_e32 v200, s4
	v_cndmask_b32_e32 v239, v239, v201, vcc
	v_cndmask_b32_e32 v238, v238, v200, vcc
	v_mov_b32_e32 v241, s7
	v_mov_b32_e32 v201, s5
	v_mov_b32_e32 v240, s6
	v_mov_b32_e32 v200, s4
	v_cndmask_b32_e32 v241, v241, v201, vcc
	v_cndmask_b32_e32 v240, v240, v200, vcc
	v_lshl_add_u64 v[238:239], v[238:239], 0, v[202:203]
	v_lshl_add_u64 v[240:241], v[240:241], 0, v[202:203]
	v_lshl_add_u64 v[238:239], v[238:239], 0, v[198:199]
	v_lshl_add_u64 v[240:241], v[240:241], 0, v[198:199]
	s_mov_b32 s25, s22
	s_mov_b32 s26, s24
	s_mov_b32 s100, 0x4000
	s_mov_b32 s101, 0
	s_waitcnt vmcnt(0)
	ds_read_b128 v[242:245], v188
	ds_read_b128 v[246:249], v188 offset:1088
	s_waitcnt lgkmcnt(1)
	v_mul_f32_e32 v242, v242, v208
	v_mul_f32_e32 v243, v243, v209
	v_mul_f32_e32 v244, v244, v210
	v_mul_f32_e32 v245, v245, v211
	global_atomic_add_f32 v[240:241], v242, off
	global_atomic_add_f32 v[240:241], v243, off offset:4
	global_atomic_add_f32 v[240:241], v244, off offset:8
	global_atomic_add_f32 v[240:241], v245, off offset:12
	v_lshl_add_u64 v[240:241], v[240:241], 0, s[100:101]
	ds_read_b128 v[242:245], v188 offset:2176
	s_waitcnt lgkmcnt(1)
	v_mul_f32_e32 v246, v246, v208
	v_mul_f32_e32 v247, v247, v209
	v_mul_f32_e32 v248, v248, v210
	v_mul_f32_e32 v249, v249, v211
	global_atomic_add_f32 v[240:241], v246, off
	global_atomic_add_f32 v[240:241], v247, off offset:4
	global_atomic_add_f32 v[240:241], v248, off offset:8
	global_atomic_add_f32 v[240:241], v249, off offset:12
	v_lshl_add_u64 v[240:241], v[240:241], 0, s[100:101]
	ds_read_b128 v[246:249], v188 offset:3264
	s_waitcnt lgkmcnt(1)
	v_mul_f32_e32 v242, v242, v208
	v_mul_f32_e32 v243, v243, v209
	v_mul_f32_e32 v244, v244, v210
	v_mul_f32_e32 v245, v245, v211
	global_atomic_add_f32 v[240:241], v242, off
	global_atomic_add_f32 v[240:241], v243, off offset:4
	global_atomic_add_f32 v[240:241], v244, off offset:8
	global_atomic_add_f32 v[240:241], v245, off offset:12
	v_lshl_add_u64 v[240:241], v[240:241], 0, s[100:101]
	ds_read_b128 v[242:245], v188 offset:4352
	s_waitcnt lgkmcnt(1)
	v_mul_f32_e32 v246, v246, v208
	v_mul_f32_e32 v247, v247, v209
	v_mul_f32_e32 v248, v248, v210
	v_mul_f32_e32 v249, v249, v211
	global_atomic_add_f32 v[240:241], v246, off
	global_atomic_add_f32 v[240:241], v247, off offset:4
	global_atomic_add_f32 v[240:241], v248, off offset:8
	global_atomic_add_f32 v[240:241], v249, off offset:12
	v_lshl_add_u64 v[240:241], v[240:241], 0, s[100:101]
	ds_read_b128 v[246:249], v188 offset:5440
	s_waitcnt lgkmcnt(1)
	v_mul_f32_e32 v242, v242, v208
	v_mul_f32_e32 v243, v243, v209
	v_mul_f32_e32 v244, v244, v210
	v_mul_f32_e32 v245, v245, v211
	global_atomic_add_f32 v[240:241], v242, off
	global_atomic_add_f32 v[240:241], v243, off offset:4
	global_atomic_add_f32 v[240:241], v244, off offset:8
	global_atomic_add_f32 v[240:241], v245, off offset:12
	v_lshl_add_u64 v[240:241], v[240:241], 0, s[100:101]
	ds_read_b128 v[242:245], v188 offset:6528
	s_waitcnt lgkmcnt(1)
;   DI void operator()(int m, int n, f32x4 v) const {
;     const int row = m + row0;
;     float* d = row < TL ? dl + (size_t)row * DM : dc + (size_t)(row - TL) * DM;
;     const int mi = row < TL ? (row >> 14) : 2;
;     const f32x4 g = *(const f32x4*)(gate + mi * 6144 + n);
; #pragma unroll
;     for (int j = 0; j < 4; ++j) unsafeAtomicAdd(d + n + j, g[j] * v[j]);
;   }
; template <class Epi>
; DI void gemm_phase512(const bf16_t* A, const bf16_t* Bt, int mtiles, int ntiles, int K, int Kper, int ksplit, const Epi& epi,
;                       unsigned char* smem, int bid, int nb) {
;     ...
;         for (int half = 0; half < 2; ++half) {
;           if (half) asm volatile("" ::: "memory");
; #pragma unroll
;           for (int ni = 0; ni < 2; ++ni)
; #pragma unroll
;             for (int mh = 0; mh < 2; ++mh)
; #pragma unroll
;               for (int g = 0; g < 4; ++g) {
;                 const int mi = 2 * half + mh;
;                 f32x4 v = {acc[ni][mi][4 * g], acc[ni][mi][4 * g + 1], acc[ni][mi][4 * g + 2], acc[ni][mi][4 * g + 3]};
;                 *(f32x4*)(wl + (mh * 32 + l31) * 272 + (ni * 32 + 8 * g + 4 * hh) * 4) = v;
;               }
;           asm volatile("" ::: "memory");
; #pragma unroll
;           for (int i = 0; i < 16; ++i) {
;             const int row = (lane >> 4) + 4 * i, ch = lane & 15;
;             const f32x4 v = *(const f32x4*)(wl + row * 272 + ch * 16);
;             epi(m0 + half * 64 + row, n0 + ch * 4, v);
;           }
	v_mul_f32_e32 v246, v246, v208
	v_mul_f32_e32 v247, v247, v209
	v_mul_f32_e32 v248, v248, v210
	v_mul_f32_e32 v249, v249, v211
	global_atomic_add_f32 v[240:241], v246, off
	global_atomic_add_f32 v[240:241], v247, off offset:4
	global_atomic_add_f32 v[240:241], v248, off offset:8
	global_atomic_add_f32 v[240:241], v249, off offset:12
	v_lshl_add_u64 v[240:241], v[240:241], 0, s[100:101]
	ds_read_b128 v[246:249], v188 offset:7616
	s_waitcnt lgkmcnt(1)
	v_mul_f32_e32 v242, v242, v208
	v_mul_f32_e32 v243, v243, v209
	v_mul_f32_e32 v244, v244, v210
	v_mul_f32_e32 v245, v245, v211
	global_atomic_add_f32 v[240:241], v242, off
	global_atomic_add_f32 v[240:241], v243, off offset:4
	global_atomic_add_f32 v[240:241], v244, off offset:8
	global_atomic_add_f32 v[240:241], v245, off offset:12
	v_lshl_add_u64 v[240:241], v[240:241], 0, s[100:101]
	ds_read_b128 v[242:245], v188 offset:8704
	s_waitcnt lgkmcnt(1)
	v_mul_f32_e32 v246, v246, v208
	v_mul_f32_e32 v247, v247, v209
	v_mul_f32_e32 v248, v248, v210
	v_mul_f32_e32 v249, v249, v211
	global_atomic_add_f32 v[240:241], v246, off
	global_atomic_add_f32 v[240:241], v247, off offset:4
	global_atomic_add_f32 v[240:241], v248, off offset:8
	global_atomic_add_f32 v[240:241], v249, off offset:12
	v_lshl_add_u64 v[240:241], v[240:241], 0, s[100:101]
	ds_read_b128 v[246:249], v188 offset:9792
	s_waitcnt lgkmcnt(1)
	v_mul_f32_e32 v242, v242, v208
	v_mul_f32_e32 v243, v243, v209
	v_mul_f32_e32 v244, v244, v210
	v_mul_f32_e32 v245, v245, v211
	global_atomic_add_f32 v[240:241], v242, off
	global_atomic_add_f32 v[240:241], v243, off offset:4
	global_atomic_add_f32 v[240:241], v244, off offset:8
	global_atomic_add_f32 v[240:241], v245, off offset:12
	v_lshl_add_u64 v[240:241], v[240:241], 0, s[100:101]
	ds_read_b128 v[242:245], v188 offset:10880
	s_waitcnt lgkmcnt(1)
	v_mul_f32_e32 v246, v246, v208
	v_mul_f32_e32 v247, v247, v209
	v_mul_f32_e32 v248, v248, v210
	v_mul_f32_e32 v249, v249, v211
	global_atomic_add_f32 v[240:241], v246, off
	global_atomic_add_f32 v[240:241], v247, off offset:4
	global_atomic_add_f32 v[240:241], v248, off offset:8
	global_atomic_add_f32 v[240:241], v249, off offset:12
	v_lshl_add_u64 v[240:241], v[240:241], 0, s[100:101]
	ds_read_b128 v[246:249], v188 offset:11968
	s_waitcnt lgkmcnt(1)
	v_mul_f32_e32 v242, v242, v208
	v_mul_f32_e32 v243, v243, v209
	v_mul_f32_e32 v244, v244, v210
	v_mul_f32_e32 v245, v245, v211
	global_atomic_add_f32 v[240:241], v242, off
	global_atomic_add_f32 v[240:241], v243, off offset:4
	global_atomic_add_f32 v[240:241], v244, off offset:8
	global_atomic_add_f32 v[240:241], v245, off offset:12
	v_lshl_add_u64 v[240:241], v[240:241], 0, s[100:101]
	ds_read_b128 v[242:245], v188 offset:13056
	s_waitcnt lgkmcnt(1)
	v_mul_f32_e32 v246, v246, v208
	v_mul_f32_e32 v247, v247, v209
	v_mul_f32_e32 v248, v248, v210
	v_mul_f32_e32 v249, v249, v211
	global_atomic_add_f32 v[240:241], v246, off
	global_atomic_add_f32 v[240:241], v247, off offset:4
	global_atomic_add_f32 v[240:241], v248, off offset:8
	global_atomic_add_f32 v[240:241], v249, off offset:12
	v_lshl_add_u64 v[240:241], v[240:241], 0, s[100:101]
	ds_read_b128 v[246:249], v188 offset:14144
	s_waitcnt lgkmcnt(1)
	v_mul_f32_e32 v242, v242, v208
	v_mul_f32_e32 v243, v243, v209
	v_mul_f32_e32 v244, v244, v210
	v_mul_f32_e32 v245, v245, v211
	global_atomic_add_f32 v[240:241], v242, off
	global_atomic_add_f32 v[240:241], v243, off offset:4
	global_atomic_add_f32 v[240:241], v244, off offset:8
	global_atomic_add_f32 v[240:241], v245, off offset:12
	v_lshl_add_u64 v[240:241], v[240:241], 0, s[100:101]
	ds_read_b128 v[242:245], v188 offset:15232
	s_waitcnt lgkmcnt(1)
	v_mul_f32_e32 v246, v246, v208
	v_mul_f32_e32 v247, v247, v209
	v_mul_f32_e32 v248, v248, v210
	v_mul_f32_e32 v249, v249, v211
	global_atomic_add_f32 v[240:241], v246, off
	global_atomic_add_f32 v[240:241], v247, off offset:4
	global_atomic_add_f32 v[240:241], v248, off offset:8
	global_atomic_add_f32 v[240:241], v249, off offset:12
	v_lshl_add_u64 v[240:241], v[240:241], 0, s[100:101]
	ds_read_b128 v[246:249], v188 offset:16320
	s_waitcnt lgkmcnt(1)
	v_mul_f32_e32 v242, v242, v208
	v_mul_f32_e32 v243, v243, v209
	v_mul_f32_e32 v244, v244, v210
	v_mul_f32_e32 v245, v245, v211
	global_atomic_add_f32 v[240:241], v242, off
	global_atomic_add_f32 v[240:241], v243, off offset:4
	global_atomic_add_f32 v[240:241], v244, off offset:8
	global_atomic_add_f32 v[240:241], v245, off offset:12
	v_lshl_add_u64 v[240:241], v[240:241], 0, s[100:101]
	s_waitcnt lgkmcnt(0)
	v_mul_f32_e32 v246, v246, v208
	v_mul_f32_e32 v247, v247, v209
	v_mul_f32_e32 v248, v248, v210
	v_mul_f32_e32 v249, v249, v211
	global_atomic_add_f32 v[240:241], v246, off
	global_atomic_add_f32 v[240:241], v247, off offset:4
	global_atomic_add_f32 v[240:241], v248, off offset:8
	global_atomic_add_f32 v[240:241], v249, off offset:12
	v_lshl_add_u64 v[240:241], v[240:241], 0, s[100:101]
	ds_write_b128 v187, v[48:51]
	ds_write_b128 v187, v[52:55] offset:32
	ds_write_b128 v187, v[56:59] offset:64
	ds_write_b128 v187, v[60:63] offset:96
	ds_write_b128 v187, v[32:35] offset:8704
	ds_write_b128 v187, v[36:39] offset:8736
	ds_write_b128 v187, v[40:43] offset:8768
	ds_write_b128 v187, v[44:47] offset:8800
	ds_write_b128 v187, v[16:19] offset:128
	ds_write_b128 v187, v[20:23] offset:160
	ds_write_b128 v187, v[24:27] offset:192
	ds_write_b128 v187, v[28:31] offset:224
	ds_write_b128 v187, v[0:3] offset:8832
	ds_write_b128 v187, v[4:7] offset:8864
	ds_write_b128 v187, v[8:11] offset:8896
	ds_write_b128 v187, v[12:15] offset:8928
	ds_read_b128 v[242:245], v188
	ds_read_b128 v[246:249], v188 offset:1088
	s_waitcnt lgkmcnt(1)
;   DI void operator()(int m, int n, f32x4 v) const {
;     const int row = m + row0;
;     float* d = row < TL ? dl + (size_t)row * DM : dc + (size_t)(row - TL) * DM;
;     const int mi = row < TL ? (row >> 14) : 2;
;     const f32x4 g = *(const f32x4*)(gate + mi * 6144 + n);
; #pragma unroll
;     for (int j = 0; j < 4; ++j) unsafeAtomicAdd(d + n + j, g[j] * v[j]);
;   }
; template <class Epi>
; DI void gemm_phase512(const bf16_t* A, const bf16_t* Bt, int mtiles, int ntiles, int K, int Kper, int ksplit, const Epi& epi,
;                       unsigned char* smem, int bid, int nb) {
;     ...
; #pragma unroll
;           for (int i = 0; i < 16; ++i) {
;             const int row = (lane >> 4) + 4 * i, ch = lane & 15;
;             const f32x4 v = *(const f32x4*)(wl + row * 272 + ch * 16);
;             epi(m0 + half * 64 + row, n0 + ch * 4, v);
;           }
	v_mul_f32_e32 v242, v242, v208
	v_mul_f32_e32 v243, v243, v209
	v_mul_f32_e32 v244, v244, v210
	v_mul_f32_e32 v245, v245, v211
	global_atomic_add_f32 v[240:241], v242, off
	global_atomic_add_f32 v[240:241], v243, off offset:4
	global_atomic_add_f32 v[240:241], v244, off offset:8
	global_atomic_add_f32 v[240:241], v245, off offset:12
	v_lshl_add_u64 v[240:241], v[240:241], 0, s[100:101]
	ds_read_b128 v[242:245], v188 offset:2176
	s_waitcnt lgkmcnt(1)
	v_mul_f32_e32 v246, v246, v208
	v_mul_f32_e32 v247, v247, v209
	v_mul_f32_e32 v248, v248, v210
	v_mul_f32_e32 v249, v249, v211
	global_atomic_add_f32 v[240:241], v246, off
	global_atomic_add_f32 v[240:241], v247, off offset:4
	global_atomic_add_f32 v[240:241], v248, off offset:8
	global_atomic_add_f32 v[240:241], v249, off offset:12
	v_lshl_add_u64 v[240:241], v[240:241], 0, s[100:101]
	ds_read_b128 v[246:249], v188 offset:3264
	s_waitcnt lgkmcnt(1)
	v_mul_f32_e32 v242, v242, v208
	v_mul_f32_e32 v243, v243, v209
	v_mul_f32_e32 v244, v244, v210
	v_mul_f32_e32 v245, v245, v211
	global_atomic_add_f32 v[240:241], v242, off
	global_atomic_add_f32 v[240:241], v243, off offset:4
	global_atomic_add_f32 v[240:241], v244, off offset:8
	global_atomic_add_f32 v[240:241], v245, off offset:12
	v_lshl_add_u64 v[240:241], v[240:241], 0, s[100:101]
	ds_read_b128 v[242:245], v188 offset:4352
	s_waitcnt lgkmcnt(1)
	v_mul_f32_e32 v246, v246, v208
	v_mul_f32_e32 v247, v247, v209
	v_mul_f32_e32 v248, v248, v210
	v_mul_f32_e32 v249, v249, v211
	global_atomic_add_f32 v[240:241], v246, off
	global_atomic_add_f32 v[240:241], v247, off offset:4
	global_atomic_add_f32 v[240:241], v248, off offset:8
	global_atomic_add_f32 v[240:241], v249, off offset:12
	v_lshl_add_u64 v[240:241], v[240:241], 0, s[100:101]
	ds_read_b128 v[246:249], v188 offset:5440
	s_waitcnt lgkmcnt(1)
	v_mul_f32_e32 v242, v242, v208
	v_mul_f32_e32 v243, v243, v209
	v_mul_f32_e32 v244, v244, v210
	v_mul_f32_e32 v245, v245, v211
	global_atomic_add_f32 v[240:241], v242, off
	global_atomic_add_f32 v[240:241], v243, off offset:4
	global_atomic_add_f32 v[240:241], v244, off offset:8
	global_atomic_add_f32 v[240:241], v245, off offset:12
	v_lshl_add_u64 v[240:241], v[240:241], 0, s[100:101]
	ds_read_b128 v[242:245], v188 offset:6528
	s_waitcnt lgkmcnt(1)
	v_mul_f32_e32 v246, v246, v208
	v_mul_f32_e32 v247, v247, v209
	v_mul_f32_e32 v248, v248, v210
	v_mul_f32_e32 v249, v249, v211
	global_atomic_add_f32 v[240:241], v246, off
	global_atomic_add_f32 v[240:241], v247, off offset:4
	global_atomic_add_f32 v[240:241], v248, off offset:8
	global_atomic_add_f32 v[240:241], v249, off offset:12
	v_lshl_add_u64 v[240:241], v[240:241], 0, s[100:101]
	ds_read_b128 v[246:249], v188 offset:7616
	s_waitcnt lgkmcnt(1)
	v_mul_f32_e32 v242, v242, v208
	v_mul_f32_e32 v243, v243, v209
	v_mul_f32_e32 v244, v244, v210
	v_mul_f32_e32 v245, v245, v211
	global_atomic_add_f32 v[240:241], v242, off
	global_atomic_add_f32 v[240:241], v243, off offset:4
	global_atomic_add_f32 v[240:241], v244, off offset:8
	global_atomic_add_f32 v[240:241], v245, off offset:12
	v_lshl_add_u64 v[240:241], v[240:241], 0, s[100:101]
	ds_read_b128 v[242:245], v188 offset:8704
	s_waitcnt lgkmcnt(1)
	v_mul_f32_e32 v246, v246, v208
	v_mul_f32_e32 v247, v247, v209
	v_mul_f32_e32 v248, v248, v210
	v_mul_f32_e32 v249, v249, v211
	global_atomic_add_f32 v[240:241], v246, off
	global_atomic_add_f32 v[240:241], v247, off offset:4
	global_atomic_add_f32 v[240:241], v248, off offset:8
	global_atomic_add_f32 v[240:241], v249, off offset:12
	v_lshl_add_u64 v[240:241], v[240:241], 0, s[100:101]
	ds_read_b128 v[246:249], v188 offset:9792
	s_waitcnt lgkmcnt(1)
;   DI void operator()(int m, int n, f32x4 v) const {
;     const int row = m + row0;
;     float* d = row < TL ? dl + (size_t)row * DM : dc + (size_t)(row - TL) * DM;
;     const int mi = row < TL ? (row >> 14) : 2;
;     const f32x4 g = *(const f32x4*)(gate + mi * 6144 + n);
; #pragma unroll
;     for (int j = 0; j < 4; ++j) unsafeAtomicAdd(d + n + j, g[j] * v[j]);
;   }
; template <class Epi>
; DI void gemm_phase512(const bf16_t* A, const bf16_t* Bt, int mtiles, int ntiles, int K, int Kper, int ksplit, const Epi& epi,
;                       unsigned char* smem, int bid, int nb) {
;     ...
; #pragma unroll
;           for (int i = 0; i < 16; ++i) {
;             const int row = (lane >> 4) + 4 * i, ch = lane & 15;
;             const f32x4 v = *(const f32x4*)(wl + row * 272 + ch * 16);
;             epi(m0 + half * 64 + row, n0 + ch * 4, v);
;           }
;         }
;       }
;     }
;     __syncthreads();
;     if (!more) break;
	v_mul_f32_e32 v242, v242, v208
	v_mul_f32_e32 v243, v243, v209
	v_mul_f32_e32 v244, v244, v210
	v_mul_f32_e32 v245, v245, v211
	global_atomic_add_f32 v[240:241], v242, off
	global_atomic_add_f32 v[240:241], v243, off offset:4
	global_atomic_add_f32 v[240:241], v244, off offset:8
	global_atomic_add_f32 v[240:241], v245, off offset:12
	v_lshl_add_u64 v[240:241], v[240:241], 0, s[100:101]
	ds_read_b128 v[242:245], v188 offset:10880
	s_waitcnt lgkmcnt(1)
	v_mul_f32_e32 v246, v246, v208
	v_mul_f32_e32 v247, v247, v209
	v_mul_f32_e32 v248, v248, v210
	v_mul_f32_e32 v249, v249, v211
	global_atomic_add_f32 v[240:241], v246, off
	global_atomic_add_f32 v[240:241], v247, off offset:4
	global_atomic_add_f32 v[240:241], v248, off offset:8
	global_atomic_add_f32 v[240:241], v249, off offset:12
	v_lshl_add_u64 v[240:241], v[240:241], 0, s[100:101]
	ds_read_b128 v[246:249], v188 offset:11968
	s_waitcnt lgkmcnt(1)
	v_mul_f32_e32 v242, v242, v208
	v_mul_f32_e32 v243, v243, v209
	v_mul_f32_e32 v244, v244, v210
	v_mul_f32_e32 v245, v245, v211
	global_atomic_add_f32 v[240:241], v242, off
	global_atomic_add_f32 v[240:241], v243, off offset:4
	global_atomic_add_f32 v[240:241], v244, off offset:8
	global_atomic_add_f32 v[240:241], v245, off offset:12
	v_lshl_add_u64 v[240:241], v[240:241], 0, s[100:101]
	ds_read_b128 v[242:245], v188 offset:13056
	s_waitcnt lgkmcnt(1)
	v_mul_f32_e32 v246, v246, v208
	v_mul_f32_e32 v247, v247, v209
	v_mul_f32_e32 v248, v248, v210
	v_mul_f32_e32 v249, v249, v211
	global_atomic_add_f32 v[240:241], v246, off
	global_atomic_add_f32 v[240:241], v247, off offset:4
	global_atomic_add_f32 v[240:241], v248, off offset:8
	global_atomic_add_f32 v[240:241], v249, off offset:12
	v_lshl_add_u64 v[240:241], v[240:241], 0, s[100:101]
	ds_read_b128 v[246:249], v188 offset:14144
	s_waitcnt lgkmcnt(1)
	v_mul_f32_e32 v242, v242, v208
	v_mul_f32_e32 v243, v243, v209
	v_mul_f32_e32 v244, v244, v210
	v_mul_f32_e32 v245, v245, v211
	global_atomic_add_f32 v[240:241], v242, off
	global_atomic_add_f32 v[240:241], v243, off offset:4
	global_atomic_add_f32 v[240:241], v244, off offset:8
	global_atomic_add_f32 v[240:241], v245, off offset:12
	v_lshl_add_u64 v[240:241], v[240:241], 0, s[100:101]
	ds_read_b128 v[242:245], v188 offset:15232
	s_waitcnt lgkmcnt(1)
	v_mul_f32_e32 v246, v246, v208
	v_mul_f32_e32 v247, v247, v209
	v_mul_f32_e32 v248, v248, v210
	v_mul_f32_e32 v249, v249, v211
	global_atomic_add_f32 v[240:241], v246, off
	global_atomic_add_f32 v[240:241], v247, off offset:4
	global_atomic_add_f32 v[240:241], v248, off offset:8
	global_atomic_add_f32 v[240:241], v249, off offset:12
	v_lshl_add_u64 v[240:241], v[240:241], 0, s[100:101]
	ds_read_b128 v[246:249], v188 offset:16320
	s_waitcnt lgkmcnt(1)
	v_mul_f32_e32 v242, v242, v208
	v_mul_f32_e32 v243, v243, v209
	v_mul_f32_e32 v244, v244, v210
	v_mul_f32_e32 v245, v245, v211
	global_atomic_add_f32 v[240:241], v242, off
	global_atomic_add_f32 v[240:241], v243, off offset:4
	global_atomic_add_f32 v[240:241], v244, off offset:8
	global_atomic_add_f32 v[240:241], v245, off offset:12
	v_lshl_add_u64 v[240:241], v[240:241], 0, s[100:101]
	s_waitcnt lgkmcnt(0)
	v_mul_f32_e32 v246, v246, v208
	v_mul_f32_e32 v247, v247, v209
	v_mul_f32_e32 v248, v248, v210
	v_mul_f32_e32 v249, v249, v211
	global_atomic_add_f32 v[240:241], v246, off
	global_atomic_add_f32 v[240:241], v247, off offset:4
	global_atomic_add_f32 v[240:241], v248, off offset:8
	global_atomic_add_f32 v[240:241], v249, off offset:12
	v_lshl_add_u64 v[240:241], v[240:241], 0, s[100:101]
	s_andn2_b64 vcc, exec, s[2:3]
	s_barrier
	s_cbranch_vccz .LBB0_767
